# code placement: one s_nop 0 before the attention tile loop (shifts all later code by 4 bytes), on v42
# speedup vs baseline: 1.0078x; 1.0078x over previous
; #define ATT_ISSUE(tilebase, bufbase) do { const unsigned char* _tb = (tilebase); asm volatile("" : "+s"(_tb)); _Pragma("unroll") for (int _i = 0; _i < 6; ++_i) { int _q = wave + 8 * _i; _q = _q > 44 ? 44 : _q; \
;         __builtin_amdgcn_global_load_lds((const unsigned*)(_tb + goff[_i]), (LAS unsigned*)((bufbase) + _q * 1024), 16, 0, 0); } } while (0)
; #define ATT_BAR() do { asm volatile("s_waitcnt vmcnt(0) lgkmcnt(0)" ::: "memory"); __builtin_amdgcn_s_barrier(); asm volatile("" ::: "memory"); } while (0)
; __device__ __forceinline__ void att_mfma(const Params& P, LAS unsigned char* lds, int wave) {
;     ...
;     for (int u = blockIdx.x; u < 1024; u += gridDim.x) {
;         const int bh = u & 63, r = u >> 6, kk = r >> 2, j4 = r & 3;
;         const int qb = kk == 0 ? j4 : (kk == 1 ? 15 - j4 : (kk == 2 ? 4 + j4 : 11 - j4));
;         const int b = bh >> 3, hh = bh & 7;
;         const int ntile = 4 * qb + 4, my_last = 4 * qb + w4;
;         const size_t qrow_g = (size_t)b * SEQ + qb * 256 + w4 * 64 + (wave >> 2) * 32 + q32;
;         const unsigned char* kvb = (const unsigned char*)(KV + (size_t)b * SEQ * 2560 + hh * 320);
;         ATT_ISSUE(kvb, lds);
;         bf16x8 qf[12];
;         { const bf16_t* qp = Q + qrow_g * 1536 + hh * 192 + hf * 8;
; #pragma unroll
;           for (int ks = 0; ks < 12; ++ks) qf[ks] = *(const bf16x8*)(qp + ks * 16); }
;         f32x16 o[4];
; #pragma unroll
;         for (int d = 0; d < 4; ++d)
; #pragma unroll
;             for (int i = 0; i < 16; ++i) o[d][i] = 0.f;
;         float mrun = -1e30f, lrun = 0.f;
;         bf16x8 pb[4];
; #pragma unroll
;         for (int i = 0; i < 4; ++i) pb[i] = (bf16x8){0, 0, 0, 0, 0, 0, 0, 0};
;         ATT_BAR();
; #pragma unroll
;         for (int ks = 0; ks < 12; ++ks) asm volatile("" : "+v"(qf[ks]));
.LBB0_1014:
	s_bfe_u32 s5, s73, 0x3000c
	s_and_b32 s6, s38, 7
	s_mul_i32 s5, s5, 0x1400000
	s_mulk_i32 s6, 0x280
	s_or_b32 s5, s5, s6
	s_add_u32 s10, s25, s5
	s_addc_u32 s11, s26, 0
	s_lshl_b32 s5, s39, 9
	s_lshl_b32 s51, s4, 2
	s_and_b32 s6, s5, 0x7000
	s_and_b32 s47, s39, 7
	s_add_i32 s50, s51, 4
	s_lshl_b32 s16, s4, 8
	s_mul_i32 s4, s6, 0x1400
	s_add_u32 s4, s48, s4
	s_addc_u32 s5, s49, 0
	s_mul_i32 s17, s47, 0x280
	s_add_u32 s4, s4, s17
	s_addc_u32 s5, s5, 0
	s_add_i32 s16, s16, s6
	v_add_u32_e32 v164, s16, v224
	s_mul_i32 s6, s47, 0x180
	s_mov_b32 s17, 2
	s_mov_b32 s61, 1
	s_mov_b32 s16, 0
	s_mov_b32 s74, 0
	s_movk_i32 s75, 0x6400
	s_mov_b32 s76, 0xc800
	s_mov_b32 s78, 0xc800
	s_mov_b32 s79, 0x11800
	s_mov_b32 s80, 0x16800
	s_mov_b32 s77, 0x1b800
	s_add_u32 s10, s10, 0x50000
	s_addc_u32 s11, s11, 0
	s_cmp_eq_u32 s33, 0
	s_cselect_b32 s82, s74, s78
	s_add_i32 m0, s74, s19
	v_lshl_add_u64 v[0:1], s[4:5], 0, v[144:145]
	global_load_lds_dwordx4 v[0:1], off
	s_add_i32 m0, s74, s20
	v_lshl_add_u64 v[0:1], s[4:5], 0, v[146:147]
	global_load_lds_dwordx4 v[0:1], off
	s_add_i32 m0, s74, s21
	v_lshl_add_u64 v[0:1], s[4:5], 0, v[148:149]
	global_load_lds_dwordx4 v[0:1], off
	s_add_i32 m0, s82, s22
	v_lshl_add_u64 v[0:1], s[4:5], 0, v[150:151]
	global_load_lds_dwordx4 v[0:1], off
	s_add_i32 m0, s78, s23
	v_lshl_add_u64 v[0:1], s[4:5], 0, v[156:157]
	global_load_lds_dwordx4 v[0:1], off
	s_add_i32 m0, s78, s24
	v_lshl_add_u64 v[0:1], s[4:5], 0, v[154:155]
	global_load_lds_dwordx4 v[0:1], off
	s_add_u32 s4, s4, 0x50000
	s_addc_u32 s5, s5, 0
	s_cmp_eq_u32 s33, 0
	s_cselect_b32 s82, s75, s79
	s_add_i32 m0, s75, s19
	v_lshl_add_u64 v[0:1], s[4:5], 0, v[144:145]
	global_load_lds_dwordx4 v[0:1], off
	s_add_i32 m0, s75, s20
	v_lshl_add_u64 v[0:1], s[4:5], 0, v[146:147]
	global_load_lds_dwordx4 v[0:1], off
	s_add_i32 m0, s75, s21
	v_lshl_add_u64 v[0:1], s[4:5], 0, v[148:149]
	global_load_lds_dwordx4 v[0:1], off
	s_add_i32 m0, s82, s22
	v_lshl_add_u64 v[0:1], s[4:5], 0, v[150:151]
	global_load_lds_dwordx4 v[0:1], off
	s_add_i32 m0, s79, s23
	v_lshl_add_u64 v[0:1], s[4:5], 0, v[156:157]
	global_load_lds_dwordx4 v[0:1], off
	s_add_i32 m0, s79, s24
	v_lshl_add_u64 v[0:1], s[4:5], 0, v[154:155]
	global_load_lds_dwordx4 v[0:1], off
	v_mad_u64_u32 v[0:1], s[4:5], v164, s35, v[166:167]
	v_lshl_add_u64 v[0:1], v[0:1], 0, s[6:7]
	v_lshl_add_u64 v[0:1], v[158:159], 1, v[0:1]
	flat_load_dwordx4 v[104:107], v[0:1]
	flat_load_dwordx4 v[108:111], v[0:1] offset:32
	flat_load_dwordx4 v[112:115], v[0:1] offset:64
	flat_load_dwordx4 v[116:119], v[0:1] offset:96
	flat_load_dwordx4 v[208:211], v[0:1] offset:128
	flat_load_dwordx4 v[200:203], v[0:1] offset:160
	flat_load_dwordx4 v[192:195], v[0:1] offset:192
	flat_load_dwordx4 v[184:187], v[0:1] offset:224
	flat_load_dwordx4 v[174:177], v[0:1] offset:256
	flat_load_dwordx4 v[132:135], v[0:1] offset:288
	flat_load_dwordx4 v[178:181], v[0:1] offset:320
	flat_load_dwordx4 v[138:141], v[0:1] offset:352
	s_waitcnt vmcnt(0) lgkmcnt(0)
	s_barrier
	v_lshlrev_b32_e32 v0, 7, v164
	v_mov_b32_e32 v1, v165
	v_and_b32_e32 v0, 0x7ff80, v0
	v_lshl_add_u64 v[142:143], v[162:163], 0, v[0:1]
	v_add_co_u32_e32 v246, vcc, s36, v142
	s_or_b32 s6, s51, s18
	s_nop 0
	v_addc_co_u32_e32 v247, vcc, 0, v143, vcc
	s_add_i32 s51, s6, 1
	s_mov_b32 s58, 0
	s_waitcnt vmcnt(0) lgkmcnt(0)
	s_nop 0
	v_and_b32_e32 v235, 0xffff0000, v104
	v_lshlrev_b32_e32 v234, 16, v104
	v_mul_f32_e32 v104, v235, v235
	v_and_b32_e32 v243, 0xffff0000, v105
	v_lshlrev_b32_e32 v242, 16, v105
	v_pk_fma_f32 v[104:105], v[234:235], v[234:235], v[104:105] op_sel_hi:[1,1,0]
	v_and_b32_e32 v233, 0xffff0000, v106
	v_lshlrev_b32_e32 v232, 16, v106
	v_pk_fma_f32 v[104:105], v[242:243], v[242:243], v[104:105]
	v_mul_f32_e32 v106, v243, v243
	v_pk_add_f32 v[104:105], v[106:107], v[104:105] op_sel_hi:[0,1]
	v_pk_fma_f32 v[104:105], v[232:233], v[232:233], v[104:105]
	v_mul_f32_e32 v106, v233, v233
	v_and_b32_e32 v241, 0xffff0000, v107
	v_lshlrev_b32_e32 v240, 16, v107
	v_pk_add_f32 v[104:105], v[106:107], v[104:105] op_sel_hi:[0,1]
	v_pk_fma_f32 v[104:105], v[240:241], v[240:241], v[104:105]
	v_mul_f32_e32 v106, v241, v241
	v_and_b32_e32 v219, 0xffff0000, v111
	v_lshlrev_b32_e32 v218, 16, v111
	v_and_b32_e32 v221, 0xffff0000, v110
	v_lshlrev_b32_e32 v220, 16, v110
	v_and_b32_e32 v111, 0xffff0000, v109
	v_lshlrev_b32_e32 v110, 16, v109
	v_and_b32_e32 v109, 0xffff0000, v108
	v_lshlrev_b32_e32 v108, 16, v108
	v_pk_add_f32 v[104:105], v[106:107], v[104:105] op_sel_hi:[0,1]
	v_pk_fma_f32 v[104:105], v[108:109], v[108:109], v[104:105]
	v_mul_f32_e32 v106, v109, v109
	v_pk_add_f32 v[104:105], v[106:107], v[104:105] op_sel_hi:[0,1]
	v_pk_fma_f32 v[104:105], v[110:111], v[110:111], v[104:105]
	v_mul_f32_e32 v106, v111, v111
	v_pk_add_f32 v[104:105], v[106:107], v[104:105] op_sel_hi:[0,1]
	v_pk_fma_f32 v[104:105], v[220:221], v[220:221], v[104:105]
	v_mul_f32_e32 v106, v221, v221
	v_pk_add_f32 v[104:105], v[106:107], v[104:105] op_sel_hi:[0,1]
	v_pk_fma_f32 v[104:105], v[218:219], v[218:219], v[104:105]
	v_mul_f32_e32 v106, v219, v219
	v_and_b32_e32 v215, 0xffff0000, v115
	v_lshlrev_b32_e32 v214, 16, v115
	v_and_b32_e32 v217, 0xffff0000, v114
	v_lshlrev_b32_e32 v216, 16, v114
	v_and_b32_e32 v115, 0xffff0000, v113
	v_lshlrev_b32_e32 v114, 16, v113
	v_and_b32_e32 v113, 0xffff0000, v112
	v_lshlrev_b32_e32 v112, 16, v112
	v_pk_add_f32 v[104:105], v[106:107], v[104:105] op_sel_hi:[0,1]
	v_pk_fma_f32 v[104:105], v[112:113], v[112:113], v[104:105]
	v_mul_f32_e32 v106, v113, v113
	v_pk_add_f32 v[104:105], v[106:107], v[104:105] op_sel_hi:[0,1]
	v_pk_fma_f32 v[104:105], v[114:115], v[114:115], v[104:105]
; __device__ __forceinline__ void att_mfma(const Params& P, LAS unsigned char* lds, int wave) {
;     ...
;             float qv[12][8]; float sq = 0.f;
; #pragma unroll
;             for (int ks = 0; ks < 12; ++ks)
; #pragma unroll
;                 for (int e = 0; e < 8; ++e) { qv[ks][e] = bf2f((unsigned short)qf[ks][e]); sq += qv[ks][e] * qv[ks][e]; }
;             { const auto rr = __builtin_amdgcn_permlane32_swap(__float_as_uint(sq), __float_as_uint(sq), false, false);
;               sq = __uint_as_float(rr[0]) + __uint_as_float(rr[1]); }
;             const float rs = __builtin_amdgcn_rsqf(sq * (1.f / 192.f) + EPS) * (0.07216878364870322f * 1.4426950408889634f);
;             const float* qg = (const float*)(ws + WS_SMALL) + 2048 + 8 * hf;
;             const int spos = (int)(qrow_g & (SEQ - 1));
;             const float* cM = (const float*)(ws + WS_ROPE_M) + spos * 32 + 8 * hf; const float* sM = cM + 4096 * 32;
; #pragma unroll
;             for (int ks = 0; ks < 12; ++ks) { const f32x4 g0 = *(const f32x4*)(qg + 16 * ks), g1 = *(const f32x4*)(qg + 16 * ks + 4);
	v_mul_f32_e32 v106, v115, v115
	v_pk_add_f32 v[104:105], v[106:107], v[104:105] op_sel_hi:[0,1]
	v_pk_fma_f32 v[104:105], v[216:217], v[216:217], v[104:105]
	v_mul_f32_e32 v106, v217, v217
	v_pk_add_f32 v[104:105], v[106:107], v[104:105] op_sel_hi:[0,1]
	v_pk_fma_f32 v[104:105], v[214:215], v[214:215], v[104:105]
	v_mul_f32_e32 v106, v215, v215
	v_and_b32_e32 v131, 0xffff0000, v133
	v_lshlrev_b32_e32 v130, 16, v133
	v_and_b32_e32 v127, 0xffff0000, v139
	v_lshlrev_b32_e32 v126, 16, v139
	v_and_b32_e32 v137, 0xffff0000, v132
	v_lshlrev_b32_e32 v136, 16, v132
	v_and_b32_e32 v133, 0xffff0000, v138
	v_lshlrev_b32_e32 v132, 16, v138
	v_and_b32_e32 v139, 0xffff0000, v177
	v_lshlrev_b32_e32 v138, 16, v177
	v_and_b32_e32 v171, 0xffff0000, v176
	v_lshlrev_b32_e32 v170, 16, v176
	v_and_b32_e32 v173, 0xffff0000, v175
	v_lshlrev_b32_e32 v172, 16, v175
	v_and_b32_e32 v169, 0xffff0000, v179
	v_lshlrev_b32_e32 v168, 16, v179
	v_and_b32_e32 v177, 0xffff0000, v174
	v_lshlrev_b32_e32 v176, 16, v174
	v_and_b32_e32 v175, 0xffff0000, v178
	v_lshlrev_b32_e32 v174, 16, v178
	v_and_b32_e32 v179, 0xffff0000, v187
	v_lshlrev_b32_e32 v178, 16, v187
	v_and_b32_e32 v183, 0xffff0000, v186
	v_lshlrev_b32_e32 v182, 16, v186
	v_and_b32_e32 v187, 0xffff0000, v195
	v_lshlrev_b32_e32 v186, 16, v195
	v_and_b32_e32 v191, 0xffff0000, v194
	v_lshlrev_b32_e32 v190, 16, v194
	v_and_b32_e32 v195, 0xffff0000, v203
	v_lshlrev_b32_e32 v194, 16, v203
	v_and_b32_e32 v199, 0xffff0000, v202
	v_lshlrev_b32_e32 v198, 16, v202
	v_and_b32_e32 v203, 0xffff0000, v211
	v_lshlrev_b32_e32 v202, 16, v211
	v_and_b32_e32 v207, 0xffff0000, v210
	v_lshlrev_b32_e32 v206, 16, v210
	v_and_b32_e32 v211, 0xffff0000, v119
	v_lshlrev_b32_e32 v210, 16, v119
	v_and_b32_e32 v213, 0xffff0000, v118
	v_lshlrev_b32_e32 v212, 16, v118
	v_and_b32_e32 v119, 0xffff0000, v117
	v_lshlrev_b32_e32 v118, 16, v117
	v_and_b32_e32 v117, 0xffff0000, v116
	v_lshlrev_b32_e32 v116, 16, v116
	v_pk_add_f32 v[104:105], v[106:107], v[104:105] op_sel_hi:[0,1]
	v_pk_fma_f32 v[104:105], v[116:117], v[116:117], v[104:105]
	v_mul_f32_e32 v106, v117, v117
	v_pk_add_f32 v[104:105], v[106:107], v[104:105] op_sel_hi:[0,1]
	v_pk_fma_f32 v[104:105], v[118:119], v[118:119], v[104:105]
	v_mul_f32_e32 v106, v119, v119
	v_pk_add_f32 v[104:105], v[106:107], v[104:105] op_sel_hi:[0,1]
	v_pk_fma_f32 v[104:105], v[212:213], v[212:213], v[104:105]
	v_mul_f32_e32 v106, v213, v213
	v_pk_add_f32 v[104:105], v[106:107], v[104:105] op_sel_hi:[0,1]
	v_pk_fma_f32 v[104:105], v[210:211], v[210:211], v[104:105]
	v_mul_f32_e32 v106, v211, v211
	v_and_b32_e32 v205, 0xffff0000, v209
	v_lshlrev_b32_e32 v204, 16, v209
	v_and_b32_e32 v209, 0xffff0000, v208
	v_lshlrev_b32_e32 v208, 16, v208
	v_pk_add_f32 v[104:105], v[106:107], v[104:105] op_sel_hi:[0,1]
	v_pk_fma_f32 v[104:105], v[208:209], v[208:209], v[104:105]
	v_mul_f32_e32 v106, v209, v209
	v_pk_add_f32 v[104:105], v[106:107], v[104:105] op_sel_hi:[0,1]
	v_pk_fma_f32 v[104:105], v[204:205], v[204:205], v[104:105]
	v_mul_f32_e32 v106, v205, v205
	v_pk_add_f32 v[104:105], v[106:107], v[104:105] op_sel_hi:[0,1]
	v_pk_fma_f32 v[104:105], v[206:207], v[206:207], v[104:105]
	v_mul_f32_e32 v106, v207, v207
	v_pk_add_f32 v[104:105], v[106:107], v[104:105] op_sel_hi:[0,1]
	v_pk_fma_f32 v[104:105], v[202:203], v[202:203], v[104:105]
	v_mul_f32_e32 v106, v203, v203
	v_and_b32_e32 v197, 0xffff0000, v201
	v_lshlrev_b32_e32 v196, 16, v201
	v_and_b32_e32 v201, 0xffff0000, v200
	v_lshlrev_b32_e32 v200, 16, v200
	v_pk_add_f32 v[104:105], v[106:107], v[104:105] op_sel_hi:[0,1]
	v_pk_fma_f32 v[104:105], v[200:201], v[200:201], v[104:105]
	v_mul_f32_e32 v106, v201, v201
	v_pk_add_f32 v[104:105], v[106:107], v[104:105] op_sel_hi:[0,1]
	v_pk_fma_f32 v[104:105], v[196:197], v[196:197], v[104:105]
	v_mul_f32_e32 v106, v197, v197
	v_pk_add_f32 v[104:105], v[106:107], v[104:105] op_sel_hi:[0,1]
	v_pk_fma_f32 v[104:105], v[198:199], v[198:199], v[104:105]
	v_mul_f32_e32 v106, v199, v199
	v_pk_add_f32 v[104:105], v[106:107], v[104:105] op_sel_hi:[0,1]
	v_pk_fma_f32 v[104:105], v[194:195], v[194:195], v[104:105]
	v_mul_f32_e32 v106, v195, v195
	v_and_b32_e32 v189, 0xffff0000, v193
	v_lshlrev_b32_e32 v188, 16, v193
	v_and_b32_e32 v193, 0xffff0000, v192
	v_lshlrev_b32_e32 v192, 16, v192
	v_pk_add_f32 v[104:105], v[106:107], v[104:105] op_sel_hi:[0,1]
	v_pk_fma_f32 v[104:105], v[192:193], v[192:193], v[104:105]
	v_mul_f32_e32 v106, v193, v193
	flat_load_dwordx4 v[100:103], v[160:161]
	flat_load_dwordx4 v[96:99], v[160:161] offset:16
	flat_load_dwordx4 v[92:95], v[160:161] offset:64
	flat_load_dwordx4 v[88:91], v[160:161] offset:80
	flat_load_dwordx4 v[84:87], v[160:161] offset:128
	flat_load_dwordx4 v[80:83], v[160:161] offset:144
	flat_load_dwordx4 v[76:79], v[160:161] offset:192
	flat_load_dwordx4 v[72:75], v[160:161] offset:208
	flat_load_dwordx4 v[68:71], v[160:161] offset:256
	flat_load_dwordx4 v[64:67], v[160:161] offset:272
	flat_load_dwordx4 v[60:63], v[160:161] offset:320
	flat_load_dwordx4 v[56:59], v[160:161] offset:336
	flat_load_dwordx4 v[52:55], v[160:161] offset:384
	flat_load_dwordx4 v[48:51], v[160:161] offset:400
	flat_load_dwordx4 v[44:47], v[160:161] offset:448
	flat_load_dwordx4 v[40:43], v[160:161] offset:464
	flat_load_dwordx4 v[36:39], v[160:161] offset:512
	flat_load_dwordx4 v[32:35], v[160:161] offset:528
	flat_load_dwordx4 v[28:31], v[160:161] offset:576
	flat_load_dwordx4 v[24:27], v[160:161] offset:592
	flat_load_dwordx4 v[20:23], v[160:161] offset:640
	flat_load_dwordx4 v[16:19], v[160:161] offset:656
	flat_load_dwordx4 v[12:15], v[160:161] offset:704
	flat_load_dwordx4 v[8:11], v[160:161] offset:720
; __device__ __forceinline__ void att_mfma(const Params& P, LAS unsigned char* lds, int wave) {
;     ...
;             float qv[12][8]; float sq = 0.f;
; #pragma unroll
;             for (int ks = 0; ks < 12; ++ks)
; #pragma unroll
;                 for (int e = 0; e < 8; ++e) { qv[ks][e] = bf2f((unsigned short)qf[ks][e]); sq += qv[ks][e] * qv[ks][e]; }
;             { const auto rr = __builtin_amdgcn_permlane32_swap(__float_as_uint(sq), __float_as_uint(sq), false, false);
;               sq = __uint_as_float(rr[0]) + __uint_as_float(rr[1]); }
;             const float rs = __builtin_amdgcn_rsqf(sq * (1.f / 192.f) + EPS) * (0.07216878364870322f * 1.4426950408889634f);
;             const float* qg = (const float*)(ws + WS_SMALL) + 2048 + 8 * hf;
;             const int spos = (int)(qrow_g & (SEQ - 1));
;             const float* cM = (const float*)(ws + WS_ROPE_M) + spos * 32 + 8 * hf; const float* sM = cM + 4096 * 32;
; #pragma unroll
;             for (int ks = 0; ks < 12; ++ks) { const f32x4 g0 = *(const f32x4*)(qg + 16 * ks), g1 = *(const f32x4*)(qg + 16 * ks + 4);
; #pragma unroll
;                 for (int e = 0; e < 4; ++e) { qv[ks][e] *= rs * g0[e]; qv[ks][4 + e] *= rs * g1[e]; } }
; #pragma unroll
;             for (int k2 = 0; k2 < 2; ++k2) {
;                 const f32x4 c0 = *(const f32x4*)(cM + 16 * k2), c1 = *(const f32x4*)(cM + 16 * k2 + 4), s0 = *(const f32x4*)(sM + 16 * k2), s1 = *(const f32x4*)(sM + 16 * k2 + 4);
	flat_load_dwordx4 v[4:7], v[142:143]
	flat_load_dwordx4 v[0:3], v[142:143] offset:16
	v_pk_add_f32 v[104:105], v[106:107], v[104:105] op_sel_hi:[0,1]
	v_pk_fma_f32 v[104:105], v[188:189], v[188:189], v[104:105]
	v_mul_f32_e32 v106, v189, v189
	v_pk_add_f32 v[104:105], v[106:107], v[104:105] op_sel_hi:[0,1]
	v_pk_fma_f32 v[104:105], v[190:191], v[190:191], v[104:105]
	v_mul_f32_e32 v106, v191, v191
	v_pk_add_f32 v[104:105], v[106:107], v[104:105] op_sel_hi:[0,1]
	v_pk_fma_f32 v[104:105], v[186:187], v[186:187], v[104:105]
	v_mul_f32_e32 v106, v187, v187
	v_and_b32_e32 v123, 0xffff0000, v135
	v_lshlrev_b32_e32 v122, 16, v135
	v_and_b32_e32 v121, 0xffff0000, v141
	v_lshlrev_b32_e32 v120, 16, v141
	v_and_b32_e32 v129, 0xffff0000, v134
	v_lshlrev_b32_e32 v128, 16, v134
	v_and_b32_e32 v125, 0xffff0000, v140
	v_lshlrev_b32_e32 v124, 16, v140
	v_and_b32_e32 v135, 0xffff0000, v181
	v_lshlrev_b32_e32 v134, 16, v181
	v_and_b32_e32 v141, 0xffff0000, v180
	v_lshlrev_b32_e32 v140, 16, v180
	v_and_b32_e32 v181, 0xffff0000, v185
	v_lshlrev_b32_e32 v180, 16, v185
	v_and_b32_e32 v185, 0xffff0000, v184
	v_lshlrev_b32_e32 v184, 16, v184
	v_pk_add_f32 v[104:105], v[106:107], v[104:105] op_sel_hi:[0,1]
	v_pk_fma_f32 v[104:105], v[184:185], v[184:185], v[104:105]
	v_mul_f32_e32 v106, v185, v185
	v_pk_add_f32 v[104:105], v[106:107], v[104:105] op_sel_hi:[0,1]
	v_pk_fma_f32 v[104:105], v[180:181], v[180:181], v[104:105]
	v_mul_f32_e32 v106, v181, v181
	v_pk_add_f32 v[104:105], v[106:107], v[104:105] op_sel_hi:[0,1]
	v_pk_fma_f32 v[104:105], v[182:183], v[182:183], v[104:105]
	v_mul_f32_e32 v106, v183, v183
	v_pk_add_f32 v[104:105], v[106:107], v[104:105] op_sel_hi:[0,1]
	v_pk_fma_f32 v[104:105], v[178:179], v[178:179], v[104:105]
	v_mul_f32_e32 v106, v179, v179
	v_pk_add_f32 v[104:105], v[106:107], v[104:105] op_sel_hi:[0,1]
	v_pk_fma_f32 v[104:105], v[176:177], v[176:177], v[104:105]
	v_mul_f32_e32 v106, v177, v177
	v_pk_add_f32 v[104:105], v[106:107], v[104:105] op_sel_hi:[0,1]
	v_pk_fma_f32 v[104:105], v[172:173], v[172:173], v[104:105]
	v_mul_f32_e32 v106, v173, v173
	v_pk_add_f32 v[104:105], v[106:107], v[104:105] op_sel_hi:[0,1]
	v_pk_fma_f32 v[104:105], v[170:171], v[170:171], v[104:105]
	v_mul_f32_e32 v106, v171, v171
	v_pk_add_f32 v[104:105], v[106:107], v[104:105] op_sel_hi:[0,1]
	v_pk_fma_f32 v[104:105], v[138:139], v[138:139], v[104:105]
	v_mul_f32_e32 v106, v139, v139
	v_pk_add_f32 v[104:105], v[106:107], v[104:105] op_sel_hi:[0,1]
	v_pk_fma_f32 v[104:105], v[136:137], v[136:137], v[104:105]
	v_mul_f32_e32 v106, v137, v137
	v_pk_add_f32 v[104:105], v[106:107], v[104:105] op_sel_hi:[0,1]
	v_pk_fma_f32 v[104:105], v[130:131], v[130:131], v[104:105]
	v_mul_f32_e32 v106, v131, v131
	v_pk_add_f32 v[104:105], v[106:107], v[104:105] op_sel_hi:[0,1]
	v_pk_fma_f32 v[104:105], v[128:129], v[128:129], v[104:105]
	v_mul_f32_e32 v106, v129, v129
	v_pk_add_f32 v[104:105], v[106:107], v[104:105] op_sel_hi:[0,1]
	v_pk_fma_f32 v[104:105], v[122:123], v[122:123], v[104:105]
	v_mul_f32_e32 v106, v123, v123
	v_pk_add_f32 v[104:105], v[106:107], v[104:105] op_sel_hi:[0,1]
	v_pk_fma_f32 v[104:105], v[174:175], v[174:175], v[104:105]
	v_mul_f32_e32 v106, v175, v175
	v_pk_add_f32 v[104:105], v[106:107], v[104:105] op_sel_hi:[0,1]
	v_pk_fma_f32 v[104:105], v[168:169], v[168:169], v[104:105]
	v_mul_f32_e32 v106, v169, v169
	v_pk_add_f32 v[104:105], v[106:107], v[104:105] op_sel_hi:[0,1]
	v_pk_fma_f32 v[104:105], v[140:141], v[140:141], v[104:105]
	v_mul_f32_e32 v106, v141, v141
	v_pk_add_f32 v[104:105], v[106:107], v[104:105] op_sel_hi:[0,1]
	v_pk_fma_f32 v[104:105], v[134:135], v[134:135], v[104:105]
	v_mul_f32_e32 v106, v135, v135
	v_pk_add_f32 v[104:105], v[106:107], v[104:105] op_sel_hi:[0,1]
	v_pk_fma_f32 v[104:105], v[132:133], v[132:133], v[104:105]
	v_mul_f32_e32 v106, v133, v133
	v_pk_add_f32 v[104:105], v[106:107], v[104:105] op_sel_hi:[0,1]
	v_pk_fma_f32 v[104:105], v[126:127], v[126:127], v[104:105]
	v_mul_f32_e32 v106, v127, v127
	v_pk_add_f32 v[104:105], v[106:107], v[104:105] op_sel_hi:[0,1]
	v_pk_fma_f32 v[104:105], v[124:125], v[124:125], v[104:105]
	v_mul_f32_e32 v106, v125, v125
	v_pk_add_f32 v[104:105], v[106:107], v[104:105] op_sel_hi:[0,1]
	v_pk_fma_f32 v[104:105], v[120:121], v[120:121], v[104:105]
	v_mul_f32_e32 v106, v121, v121
	v_pk_add_f32 v[104:105], v[106:107], v[104:105] op_sel_hi:[0,1]
	v_mov_b32_e32 v105, v104
	s_nop 1
	v_permlane32_swap_b32_e32 v104, v105
	v_add_f32_e32 v104, v104, v105
	v_fmamk_f32 v104, v104, 0x3baaaaab, v225
	v_rsq_f32_e32 v227, v104
	flat_load_dwordx4 v[104:107], v[246:247]
	flat_load_dwordx4 v[228:231], v[246:247] offset:16
	v_mul_f32_e32 v248, 0x3dd53b94, v227
	s_waitcnt vmcnt(0) lgkmcnt(0)
; __device__ __forceinline__ void att_mfma(const Params& P, LAS unsigned char* lds, int wave) {
;     ...
; #pragma unroll
;             for (int ks = 0; ks < 12; ++ks) { const f32x4 g0 = *(const f32x4*)(qg + 16 * ks), g1 = *(const f32x4*)(qg + 16 * ks + 4);
; #pragma unroll
;                 for (int e = 0; e < 4; ++e) { qv[ks][e] *= rs * g0[e]; qv[ks][4 + e] *= rs * g1[e]; } }
; #pragma unroll
;             for (int k2 = 0; k2 < 2; ++k2) {
;                 const f32x4 c0 = *(const f32x4*)(cM + 16 * k2), c1 = *(const f32x4*)(cM + 16 * k2 + 4), s0 = *(const f32x4*)(sM + 16 * k2), s1 = *(const f32x4*)(sM + 16 * k2 + 4);
; #pragma unroll
;                 for (int e = 0; e < 8; ++e) { const float cc = e < 4 ? c0[e & 3] : c1[e & 3], ss = e < 4 ? s0[e & 3] : s1[e & 3];
;                     const float a = qv[8 + k2][e], bq = qv[10 + k2][e]; qv[8 + k2][e] = a * cc - bq * ss; qv[10 + k2][e] = bq * cc + a * ss; }
;             }
	v_pk_mul_f32 v[96:97], v[96:97], v[248:249] op_sel_hi:[1,0]
	v_pk_mul_f32 v[100:101], v[100:101], v[248:249] op_sel_hi:[1,0]
	v_pk_mul_f32 v[252:253], v[96:97], v[232:233]
	v_pk_mul_f32 v[96:97], v[102:103], v[248:249] op_sel_hi:[1,0]
	v_pk_mul_f32 v[250:251], v[100:101], v[234:235]
	flat_load_dwordx4 v[232:235], v[142:143] offset:64
	flat_load_dwordx4 v[236:239], v[142:143] offset:80
	v_pk_mul_f32 v[142:143], v[96:97], v[242:243]
	v_pk_mul_f32 v[242:243], v[98:99], v[248:249] op_sel_hi:[1,0]
	flat_load_dwordx4 v[96:99], v[246:247] offset:64
	flat_load_dwordx4 v[100:103], v[246:247] offset:80
	v_pk_mul_f32 v[20:21], v[248:249], v[20:21] op_sel_hi:[0,1]
	v_pk_mul_f32 v[92:93], v[92:93], v[248:249] op_sel_hi:[1,0]
	v_pk_mul_f32 v[36:37], v[248:249], v[36:37] op_sel_hi:[0,1]
	v_pk_mul_f32 v[20:21], v[20:21], v[174:175]
	v_pk_mul_f32 v[92:93], v[92:93], v[108:109]
	v_pk_mul_f32 v[36:37], v[36:37], v[176:177]
	v_pk_mul_f32 v[38:39], v[248:249], v[38:39] op_sel_hi:[0,1]
	v_pk_mul_f32 v[24:25], v[248:249], v[24:25] op_sel_hi:[0,1]
	v_pk_mul_f32 v[22:23], v[248:249], v[22:23] op_sel_hi:[0,1]
	v_pk_mul_f32 v[38:39], v[38:39], v[172:173]
	v_pk_mul_f32 v[24:25], v[24:25], v[128:129]
	v_pk_mul_f32 v[16:17], v[248:249], v[16:17] op_sel_hi:[0,1]
	v_pk_mul_f32 v[22:23], v[22:23], v[168:169]
	v_pk_mul_f32 v[32:33], v[248:249], v[32:33] op_sel_hi:[0,1]
	v_pk_mul_f32 v[16:17], v[16:17], v[140:141]
	v_pk_mul_f32 v[32:33], v[32:33], v[170:171]
	v_pk_mul_f32 v[34:35], v[248:249], v[34:35] op_sel_hi:[0,1]
	v_pk_mul_f32 v[18:19], v[248:249], v[18:19] op_sel_hi:[0,1]
	v_pk_mul_f32 v[34:35], v[34:35], v[138:139]
	v_pk_mul_f32 v[18:19], v[18:19], v[134:135]
	v_pk_mul_f32 v[12:13], v[248:249], v[12:13] op_sel_hi:[0,1]
	v_pk_mul_f32 v[28:29], v[248:249], v[28:29] op_sel_hi:[0,1]
	v_pk_mul_f32 v[12:13], v[12:13], v[132:133]
	v_pk_mul_f32 v[28:29], v[28:29], v[136:137]
	v_pk_mul_f32 v[14:15], v[248:249], v[14:15] op_sel_hi:[0,1]
	v_pk_mul_f32 v[30:31], v[248:249], v[30:31] op_sel_hi:[0,1]
	v_pk_mul_f32 v[14:15], v[14:15], v[126:127]
	v_pk_mul_f32 v[30:31], v[30:31], v[130:131]
	v_pk_mul_f32 v[8:9], v[248:249], v[8:9] op_sel_hi:[0,1]
	v_pk_mul_f32 v[8:9], v[8:9], v[124:125]
	v_pk_mul_f32 v[10:11], v[248:249], v[10:11] op_sel_hi:[0,1]
	v_pk_mul_f32 v[26:27], v[248:249], v[26:27] op_sel_hi:[0,1]
	v_pk_mul_f32 v[10:11], v[10:11], v[120:121]
	v_pk_mul_f32 v[26:27], v[26:27], v[122:123]
	v_pk_mul_f32 v[60:61], v[248:249], v[60:61] op_sel_hi:[0,1]
	v_pk_mul_f32 v[56:57], v[248:249], v[56:57] op_sel_hi:[0,1]
	v_pk_mul_f32 v[62:63], v[248:249], v[62:63] op_sel_hi:[0,1]
	v_pk_mul_f32 v[58:59], v[248:249], v[58:59] op_sel_hi:[0,1]
	v_pk_mul_f32 v[52:53], v[248:249], v[52:53] op_sel_hi:[0,1]
	v_pk_mul_f32 v[48:49], v[248:249], v[48:49] op_sel_hi:[0,1]
	v_pk_mul_f32 v[54:55], v[248:249], v[54:55] op_sel_hi:[0,1]
	v_pk_mul_f32 v[50:51], v[248:249], v[50:51] op_sel_hi:[0,1]
	v_pk_mul_f32 v[44:45], v[248:249], v[44:45] op_sel_hi:[0,1]
	v_pk_mul_f32 v[40:41], v[248:249], v[40:41] op_sel_hi:[0,1]
	v_pk_mul_f32 v[46:47], v[248:249], v[46:47] op_sel_hi:[0,1]
	v_pk_mul_f32 v[42:43], v[248:249], v[42:43] op_sel_hi:[0,1]
	v_pk_mul_f32 v[88:89], v[88:89], v[248:249] op_sel_hi:[1,0]
	v_pk_mul_f32 v[94:95], v[94:95], v[248:249] op_sel_hi:[1,0]
	v_pk_mul_f32 v[90:91], v[90:91], v[248:249] op_sel_hi:[1,0]
	v_pk_mul_f32 v[84:85], v[84:85], v[248:249] op_sel_hi:[1,0]
	v_pk_mul_f32 v[80:81], v[248:249], v[80:81] op_sel_hi:[0,1]
	v_pk_mul_f32 v[86:87], v[86:87], v[248:249] op_sel_hi:[1,0]
	v_pk_mul_f32 v[82:83], v[248:249], v[82:83] op_sel_hi:[0,1]
	v_pk_mul_f32 v[76:77], v[248:249], v[76:77] op_sel_hi:[0,1]
	v_pk_mul_f32 v[72:73], v[248:249], v[72:73] op_sel_hi:[0,1]
	v_pk_mul_f32 v[78:79], v[248:249], v[78:79] op_sel_hi:[0,1]
	v_pk_mul_f32 v[74:75], v[248:249], v[74:75] op_sel_hi:[0,1]
	v_pk_mul_f32 v[68:69], v[248:249], v[68:69] op_sel_hi:[0,1]
	v_pk_mul_f32 v[64:65], v[248:249], v[64:65] op_sel_hi:[0,1]
	v_pk_mul_f32 v[70:71], v[248:249], v[70:71] op_sel_hi:[0,1]
	v_pk_mul_f32 v[66:67], v[248:249], v[66:67] op_sel_hi:[0,1]
	v_pk_mul_f32 v[60:61], v[60:61], v[200:201]
	v_pk_mul_f32 v[56:57], v[56:57], v[198:199]
	v_pk_mul_f32 v[62:63], v[62:63], v[196:197]
	v_pk_mul_f32 v[58:59], v[58:59], v[194:195]
	v_pk_mul_f32 v[52:53], v[52:53], v[192:193]
	v_pk_mul_f32 v[108:109], v[20:21], v[104:105]
	v_pk_mul_f32 v[48:49], v[48:49], v[190:191]
	v_pk_fma_f32 v[128:129], v[36:37], v[4:5], v[108:109] neg_lo:[0,0,1] neg_hi:[0,0,1]
	v_pk_mul_f32 v[36:37], v[36:37], v[104:105]
	v_pk_mul_f32 v[54:55], v[54:55], v[188:189]
	v_pk_fma_f32 v[4:5], v[20:21], v[4:5], v[36:37]
	v_pk_mul_f32 v[20:21], v[22:23], v[106:107]
	v_pk_mul_f32 v[36:37], v[38:39], v[106:107]
	v_pk_fma_f32 v[20:21], v[38:39], v[6:7], v[20:21] neg_lo:[0,0,1] neg_hi:[0,0,1]
	v_pk_fma_f32 v[6:7], v[22:23], v[6:7], v[36:37]
	v_pk_mul_f32 v[22:23], v[16:17], v[228:229]
	v_pk_mul_f32 v[50:51], v[50:51], v[186:187]
	v_pk_fma_f32 v[22:23], v[32:33], v[0:1], v[22:23] neg_lo:[0,0,1] neg_hi:[0,0,1]
	v_pk_mul_f32 v[32:33], v[32:33], v[228:229]
	v_pk_mul_f32 v[44:45], v[44:45], v[184:185]
	v_pk_fma_f32 v[0:1], v[16:17], v[0:1], v[32:33]
	v_pk_mul_f32 v[16:17], v[18:19], v[230:231]
	v_pk_mul_f32 v[32:33], v[34:35], v[230:231]
	v_pk_fma_f32 v[16:17], v[34:35], v[2:3], v[16:17] neg_lo:[0,0,1] neg_hi:[0,0,1]
	v_pk_fma_f32 v[2:3], v[18:19], v[2:3], v[32:33]
	s_waitcnt vmcnt(0) lgkmcnt(0)
; __device__ __forceinline__ void att_mfma(const Params& P, LAS unsigned char* lds, int wave) {
;     ...
;         f32x16 o[4];
; #pragma unroll
;         for (int d = 0; d < 4; ++d)
; #pragma unroll
;             for (int i = 0; i < 16; ++i) o[d][i] = 0.f;
;         float mrun = -1e30f, lrun = 0.f;
;         bf16x8 pb[4];
; #pragma unroll
;         for (int i = 0; i < 4; ++i) pb[i] = (bf16x8){0, 0, 0, 0, 0, 0, 0, 0};
;         ATT_BAR();
; #pragma unroll
;         for (int ks = 0; ks < 12; ++ks) asm volatile("" : "+v"(qf[ks]));
;         {
;             float qv[12][8]; float sq = 0.f;
; #pragma unroll
;             for (int ks = 0; ks < 12; ++ks)
; #pragma unroll
;                 for (int e = 0; e < 8; ++e) { qv[ks][e] = bf2f((unsigned short)qf[ks][e]); sq += qv[ks][e] * qv[ks][e]; }
;             { const auto rr = __builtin_amdgcn_permlane32_swap(__float_as_uint(sq), __float_as_uint(sq), false, false);
;               sq = __uint_as_float(rr[0]) + __uint_as_float(rr[1]); }
;             const float rs = __builtin_amdgcn_rsqf(sq * (1.f / 192.f) + EPS) * (0.07216878364870322f * 1.4426950408889634f);
;             const float* qg = (const float*)(ws + WS_SMALL) + 2048 + 8 * hf;
;             const int spos = (int)(qrow_g & (SEQ - 1));
;             const float* cM = (const float*)(ws + WS_ROPE_M) + spos * 32 + 8 * hf; const float* sM = cM + 4096 * 32;
; #pragma unroll
;             for (int ks = 0; ks < 12; ++ks) { const f32x4 g0 = *(const f32x4*)(qg + 16 * ks), g1 = *(const f32x4*)(qg + 16 * ks + 4);
; #pragma unroll
;                 for (int e = 0; e < 4; ++e) { qv[ks][e] *= rs * g0[e]; qv[ks][4 + e] *= rs * g1[e]; } }
; #pragma unroll
;             for (int k2 = 0; k2 < 2; ++k2) {
;                 const f32x4 c0 = *(const f32x4*)(cM + 16 * k2), c1 = *(const f32x4*)(cM + 16 * k2 + 4), s0 = *(const f32x4*)(sM + 16 * k2), s1 = *(const f32x4*)(sM + 16 * k2 + 4);
; #pragma unroll
;                 for (int e = 0; e < 8; ++e) { const float cc = e < 4 ? c0[e & 3] : c1[e & 3], ss = e < 4 ? s0[e & 3] : s1[e & 3];
;                     const float a = qv[8 + k2][e], bq = qv[10 + k2][e]; qv[8 + k2][e] = a * cc - bq * ss; qv[10 + k2][e] = bq * cc + a * ss; }
;             }
; #pragma unroll
;             for (int ks = 0; ks < 12; ++ks) qf[ks] = pack8bf(qv[ks][0], qv[ks][1], qv[ks][2], qv[ks][3], qv[ks][4], qv[ks][5], qv[ks][6], qv[ks][7]);
;         }
	v_pk_mul_f32 v[18:19], v[12:13], v[96:97]
	v_pk_mul_f32 v[40:41], v[40:41], v[182:183]
	v_pk_fma_f32 v[18:19], v[28:29], v[232:233], v[18:19] neg_lo:[0,0,1] neg_hi:[0,0,1]
	v_pk_mul_f32 v[28:29], v[28:29], v[96:97]
	v_pk_mul_f32 v[46:47], v[46:47], v[180:181]
	v_pk_fma_f32 v[12:13], v[12:13], v[232:233], v[28:29]
	v_pk_mul_f32 v[28:29], v[14:15], v[98:99]
	v_pk_mul_f32 v[42:43], v[42:43], v[178:179]
	v_pk_fma_f32 v[28:29], v[30:31], v[234:235], v[28:29] neg_lo:[0,0,1] neg_hi:[0,0,1]
	v_pk_mul_f32 v[30:31], v[30:31], v[98:99]
	v_pk_mul_f32 v[240:241], v[242:243], v[240:241]
	v_pk_fma_f32 v[14:15], v[14:15], v[234:235], v[30:31]
	v_pk_mul_f32 v[30:31], v[8:9], v[100:101]
	v_cvt_pk_bf16_f32 v141, v14, v15
	v_pk_fma_f32 v[30:31], v[24:25], v[236:237], v[30:31] neg_lo:[0,0,1] neg_hi:[0,0,1]
	v_pk_mul_f32 v[24:25], v[24:25], v[100:101]
	v_mov_b32_e32 v14, v165
	v_pk_fma_f32 v[8:9], v[8:9], v[236:237], v[24:25]
	v_pk_mul_f32 v[24:25], v[10:11], v[102:103]
	v_mov_b32_e32 v15, v165
	v_pk_fma_f32 v[24:25], v[26:27], v[238:239], v[24:25] neg_lo:[0,0,1] neg_hi:[0,0,1]
	v_pk_mul_f32 v[26:27], v[26:27], v[102:103]
	v_pk_mul_f32 v[88:89], v[88:89], v[220:221]
	v_pk_fma_f32 v[10:11], v[10:11], v[238:239], v[26:27]
	v_pk_mul_f32 v[94:95], v[94:95], v[110:111]
	v_pk_mul_f32 v[90:91], v[90:91], v[218:219]
	v_pk_mul_f32 v[84:85], v[84:85], v[112:113]
	v_pk_mul_f32 v[80:81], v[80:81], v[216:217]
	v_pk_mul_f32 v[86:87], v[86:87], v[114:115]
	v_pk_mul_f32 v[82:83], v[82:83], v[214:215]
	v_pk_mul_f32 v[76:77], v[76:77], v[116:117]
	v_pk_mul_f32 v[72:73], v[72:73], v[212:213]
	v_pk_mul_f32 v[78:79], v[78:79], v[118:119]
	v_pk_mul_f32 v[74:75], v[74:75], v[210:211]
	v_pk_mul_f32 v[68:69], v[68:69], v[208:209]
	v_pk_mul_f32 v[64:65], v[64:65], v[206:207]
	v_pk_mul_f32 v[70:71], v[70:71], v[204:205]
	v_pk_mul_f32 v[66:67], v[66:67], v[202:203]
	v_cvt_pk_bf16_f32 v97, v142, v143
	v_cvt_pk_bf16_f32 v116, v60, v61
	v_cvt_pk_bf16_f32 v117, v62, v63
	v_cvt_pk_bf16_f32 v118, v56, v57
	v_cvt_pk_bf16_f32 v119, v58, v59
	v_cvt_pk_bf16_f32 v120, v52, v53
	v_cvt_pk_bf16_f32 v121, v54, v55
	v_cvt_pk_bf16_f32 v122, v48, v49
	v_cvt_pk_bf16_f32 v123, v50, v51
	v_cvt_pk_bf16_f32 v124, v44, v45
	v_cvt_pk_bf16_f32 v125, v46, v47
	v_cvt_pk_bf16_f32 v126, v40, v41
	v_cvt_pk_bf16_f32 v127, v42, v43
	v_cvt_pk_bf16_f32 v128, v128, v129
	v_cvt_pk_bf16_f32 v129, v20, v21
	v_cvt_pk_bf16_f32 v130, v22, v23
	v_cvt_pk_bf16_f32 v131, v16, v17
	v_cvt_pk_bf16_f32 v132, v18, v19
	v_cvt_pk_bf16_f32 v133, v28, v29
	v_cvt_pk_bf16_f32 v134, v30, v31
	v_cvt_pk_bf16_f32 v135, v24, v25
	v_cvt_pk_bf16_f32 v136, v4, v5
	v_cvt_pk_bf16_f32 v137, v6, v7
	v_cvt_pk_bf16_f32 v138, v0, v1
	v_cvt_pk_bf16_f32 v139, v2, v3
	v_cvt_pk_bf16_f32 v140, v12, v13
	v_cvt_pk_bf16_f32 v142, v8, v9
	v_cvt_pk_bf16_f32 v143, v10, v11
	v_mov_b32_e32 v0, v165
	v_mov_b32_e32 v1, v165
	v_mov_b32_e32 v2, v165
	v_mov_b32_e32 v3, v165
	v_mov_b32_e32 v4, v165
	v_mov_b32_e32 v5, v165
	v_mov_b32_e32 v6, v165
	v_mov_b32_e32 v7, v165
	v_mov_b32_e32 v8, v165
	v_mov_b32_e32 v9, v165
	v_mov_b32_e32 v10, v165
	v_mov_b32_e32 v11, v165
	v_mov_b32_e32 v12, v165
	v_mov_b32_e32 v13, v165
	v_mov_b64_e32 v[30:31], v[14:15]
	v_mov_b64_e32 v[46:47], v[14:15]
	v_mov_b64_e32 v[62:63], v[14:15]
	v_cvt_pk_bf16_f32 v96, v250, v251
	v_cvt_pk_bf16_f32 v98, v252, v253
	v_cvt_pk_bf16_f32 v99, v240, v241
	v_cvt_pk_bf16_f32 v100, v92, v93
	v_cvt_pk_bf16_f32 v101, v94, v95
	v_cvt_pk_bf16_f32 v102, v88, v89
	v_cvt_pk_bf16_f32 v103, v90, v91
	v_cvt_pk_bf16_f32 v104, v84, v85
	v_cvt_pk_bf16_f32 v105, v86, v87
	v_cvt_pk_bf16_f32 v106, v80, v81
	v_cvt_pk_bf16_f32 v107, v82, v83
	v_cvt_pk_bf16_f32 v108, v76, v77
	v_cvt_pk_bf16_f32 v109, v78, v79
	v_cvt_pk_bf16_f32 v110, v72, v73
	v_cvt_pk_bf16_f32 v111, v74, v75
	v_cvt_pk_bf16_f32 v112, v68, v69
	v_cvt_pk_bf16_f32 v113, v70, v71
	v_cvt_pk_bf16_f32 v114, v64, v65
	v_cvt_pk_bf16_f32 v115, v66, v67
	v_mov_b32_e32 v169, 0xf149f2ca
	v_mov_b32_e32 v168, 0
	v_mov_b32_e32 v64, 0
	v_mov_b32_e32 v65, 0
	v_mov_b32_e32 v66, 0
	v_mov_b32_e32 v67, 0
	v_mov_b32_e32 v68, 0
	v_mov_b32_e32 v69, 0
	v_mov_b32_e32 v70, 0
	v_mov_b32_e32 v71, 0
	v_mov_b32_e32 v72, 0
	v_mov_b32_e32 v73, 0
	v_mov_b32_e32 v74, 0
	v_mov_b32_e32 v75, 0
	v_mov_b32_e32 v76, 0
	v_mov_b32_e32 v77, 0
	v_mov_b32_e32 v78, 0
	v_mov_b32_e32 v79, 0
	v_mov_b64_e32 v[28:29], v[12:13]
	v_mov_b64_e32 v[26:27], v[10:11]
	v_mov_b64_e32 v[24:25], v[8:9]
	v_mov_b64_e32 v[22:23], v[6:7]
	v_mov_b64_e32 v[20:21], v[4:5]
	v_mov_b64_e32 v[18:19], v[2:3]
	v_mov_b64_e32 v[16:17], v[0:1]
	v_mov_b64_e32 v[44:45], v[12:13]
	v_mov_b64_e32 v[42:43], v[10:11]
	v_mov_b64_e32 v[40:41], v[8:9]
	v_mov_b64_e32 v[38:39], v[6:7]
	v_mov_b64_e32 v[36:37], v[4:5]
	v_mov_b64_e32 v[34:35], v[2:3]
	v_mov_b64_e32 v[32:33], v[0:1]
	v_mov_b64_e32 v[60:61], v[12:13]
	v_mov_b64_e32 v[58:59], v[10:11]
	v_mov_b64_e32 v[56:57], v[8:9]
	v_mov_b64_e32 v[54:55], v[6:7]
	v_mov_b64_e32 v[52:53], v[4:5]
	v_mov_b64_e32 v[50:51], v[2:3]
	v_mov_b64_e32 v[48:49], v[0:1]
	s_add_i32 s60, s16, 1
	s_add_i32 s81, s16, 2
	s_cmp_ge_u32 s81, s50
	s_mov_b32 s59, s61
	s_mov_b32 s83, 0
	s_cbranch_scc1 .LBB0_1016
	s_nop 0
